# GEMM K loops: per-phase s_setprio flips replaced by one static s_setprio 1 for waves 0-3 (other half than the previous version)
# baseline (speedup 1.0000x reference)
.LBB0_55:
	v_mov_b64_e32 v[2:3], 0x840
	s_ashr_i32 s25, s24, 31
	v_cmp_lt_i64_e32 vcc, s[10:11], v[2:3]
	s_lshl_b64 s[10:11], s[24:25], 19
	v_readlane_b32 s14, v254, 33
	v_readlane_b32 s15, v254, 34
	s_add_u32 s34, s14, s10
	s_addc_u32 s35, s15, s11
	v_readlane_b32 s98, v254, 0
	s_and_b32 s98, s98, s99
	s_mul_i32 s98, s98, 0x40000
	s_add_u32 s34, s34, s98
	s_addc_u32 s35, s35, 0
	s_and_b64 s[10:11], vcc, exec
	s_cselect_b32 s14, s35, s7
	s_cselect_b32 s15, s34, s6
	s_ashr_i32 s23, s22, 31
	s_lshl_b64 s[10:11], s[22:23], 19
	s_add_u32 s30, s3, s10
	s_addc_u32 s31, s42, s11
	s_and_b64 s[10:11], vcc, exec
	s_cselect_b32 s16, s31, s9
	s_cselect_b32 s17, s30, s8
	s_add_u32 s23, s8, 0x100
	s_addc_u32 s25, s9, 0
	s_add_u32 s6, s6, 0x40080
	v_mov_b32_e32 v2, 0
	s_addc_u32 s7, s7, 0
	s_mov_b32 s40, -2
	v_mov_b32_e32 v3, v2
	v_mov_b32_e32 v4, v2
	v_mov_b32_e32 v5, v2
	v_mov_b32_e32 v6, v2
	v_mov_b32_e32 v7, v2
	v_mov_b32_e32 v8, v2
	v_mov_b32_e32 v9, v2
	v_mov_b32_e32 v18, v2
	v_mov_b32_e32 v19, v2
	v_mov_b32_e32 v20, v2
	v_mov_b32_e32 v21, v2
	v_mov_b32_e32 v22, v2
	v_mov_b32_e32 v23, v2
	v_mov_b32_e32 v24, v2
	v_mov_b32_e32 v25, v2
	v_mov_b32_e32 v30, v2
	v_mov_b32_e32 v31, v2
	v_mov_b32_e32 v32, v2
	v_mov_b32_e32 v33, v2
	v_mov_b32_e32 v38, v2
	v_mov_b32_e32 v39, v2
	v_mov_b32_e32 v40, v2
	v_mov_b32_e32 v41, v2
	v_mov_b32_e32 v46, v2
	v_mov_b32_e32 v47, v2
	v_mov_b32_e32 v48, v2
	v_mov_b32_e32 v49, v2
	v_mov_b32_e32 v54, v2
	v_mov_b32_e32 v55, v2
	v_mov_b32_e32 v56, v2
	v_mov_b32_e32 v57, v2
	v_mov_b32_e32 v10, v2
	v_mov_b32_e32 v11, v2
	v_mov_b32_e32 v12, v2
	v_mov_b32_e32 v13, v2
	v_mov_b32_e32 v14, v2
	v_mov_b32_e32 v15, v2
	v_mov_b32_e32 v16, v2
	v_mov_b32_e32 v17, v2
	v_mov_b32_e32 v26, v2
	v_mov_b32_e32 v27, v2
	v_mov_b32_e32 v28, v2
	v_mov_b32_e32 v29, v2
	v_mov_b32_e32 v34, v2
	v_mov_b32_e32 v35, v2
	v_mov_b32_e32 v36, v2
	v_mov_b32_e32 v37, v2
	v_mov_b32_e32 v42, v2
	v_mov_b32_e32 v43, v2
	v_mov_b32_e32 v44, v2
	v_mov_b32_e32 v45, v2
	v_mov_b32_e32 v50, v2
	v_mov_b32_e32 v51, v2
	v_mov_b32_e32 v52, v2
	v_mov_b32_e32 v53, v2
	v_mov_b32_e32 v58, v2
	v_mov_b32_e32 v59, v2
	v_mov_b32_e32 v60, v2
	v_mov_b32_e32 v61, v2
	v_mov_b32_e32 v62, v2
	v_mov_b32_e32 v63, v2
	v_mov_b32_e32 v64, v2
	v_mov_b32_e32 v65, v2
	v_mov_b32_e32 v98, v2
	v_mov_b32_e32 v99, v2
	v_mov_b32_e32 v100, v2
	v_mov_b32_e32 v101, v2
	v_mov_b32_e32 v102, v2
	v_mov_b32_e32 v103, v2
	v_mov_b32_e32 v104, v2
	v_mov_b32_e32 v105, v2
	v_mov_b32_e32 v114, v2
	v_mov_b32_e32 v115, v2
	v_mov_b32_e32 v116, v2
	v_mov_b32_e32 v117, v2
	v_mov_b32_e32 v118, v2
	v_mov_b32_e32 v119, v2
	v_mov_b32_e32 v120, v2
	v_mov_b32_e32 v121, v2
	v_mov_b32_e32 v126, v2
	v_mov_b32_e32 v127, v2
	v_mov_b32_e32 v128, v2
	v_mov_b32_e32 v129, v2
	v_mov_b32_e32 v134, v2
	v_mov_b32_e32 v135, v2
	v_mov_b32_e32 v136, v2
	v_mov_b32_e32 v137, v2
	v_mov_b32_e32 v142, v2
	v_mov_b32_e32 v143, v2
	v_mov_b32_e32 v144, v2
	v_mov_b32_e32 v145, v2
	v_mov_b32_e32 v150, v2
	v_mov_b32_e32 v151, v2
	v_mov_b32_e32 v152, v2
	v_mov_b32_e32 v153, v2
	v_mov_b32_e32 v106, v2
	v_mov_b32_e32 v107, v2
	v_mov_b32_e32 v108, v2
	v_mov_b32_e32 v109, v2
	v_mov_b32_e32 v110, v2
	v_mov_b32_e32 v111, v2
	v_mov_b32_e32 v112, v2
	v_mov_b32_e32 v113, v2
	v_mov_b32_e32 v122, v2
	v_mov_b32_e32 v123, v2
	v_mov_b32_e32 v124, v2
	v_mov_b32_e32 v125, v2
	v_mov_b32_e32 v130, v2
	v_mov_b32_e32 v131, v2
	v_mov_b32_e32 v132, v2
	v_mov_b32_e32 v133, v2
	v_mov_b32_e32 v138, v2
	v_mov_b32_e32 v139, v2
	v_mov_b32_e32 v140, v2
	v_mov_b32_e32 v141, v2
	v_mov_b32_e32 v146, v2
	v_mov_b32_e32 v147, v2
	v_mov_b32_e32 v148, v2
	v_mov_b32_e32 v149, v2
	v_mov_b32_e32 v154, v2
	v_mov_b32_e32 v155, v2
	v_mov_b32_e32 v156, v2
	v_mov_b32_e32 v157, v2
	v_mov_b32_e32 v158, v2
	v_mov_b32_e32 v159, v2
	v_mov_b32_e32 v160, v2
	v_mov_b32_e32 v161, v2
	v_readlane_b32 s99, v255, 41
	s_cmp_eq_u32 s52, 9
	s_cselect_b32 s99, s99, 0
	v_cmp_gt_u32_e32 vcc, 0x100, v163
	s_nop 1
	s_cbranch_vccz .Lsprio_skip0
	s_setprio 1

.LBB0_345:
	s_ashr_i32 s15, s14, 31
	v_cmp_lt_i64_e32 vcc, s[16:17], v[166:167]
	s_lshl_b64 s[16:17], s[14:15], 19
	v_readlane_b32 s18, v254, 33
	v_readlane_b32 s19, v254, 34
	s_add_u32 s16, s18, s16
	s_addc_u32 s17, s19, s17
	s_and_b64 s[18:19], vcc, exec
	s_cselect_b32 s15, s17, s23
	s_cselect_b32 s45, s16, s22
	s_ashr_i32 s13, s12, 31
	s_lshl_b64 s[18:19], s[12:13], 19
	s_add_u32 s18, s3, s18
	s_addc_u32 s19, s30, s19
	s_and_b64 s[26:27], vcc, exec
	s_cselect_b32 s13, s19, s25
	s_cselect_b32 s46, s18, s24
	s_add_u32 s47, s24, 0x100
	v_mov_b32_e32 v2, 0
	s_addc_u32 s48, s25, 0
	s_mov_b32 s49, -2
	v_mov_b32_e32 v3, v2
	v_mov_b32_e32 v4, v2
	v_mov_b32_e32 v5, v2
	v_mov_b32_e32 v6, v2
	v_mov_b32_e32 v7, v2
	v_mov_b32_e32 v8, v2
	v_mov_b32_e32 v9, v2
	v_mov_b32_e32 v10, v2
	v_mov_b32_e32 v11, v2
	v_mov_b32_e32 v12, v2
	v_mov_b32_e32 v13, v2
	v_mov_b32_e32 v14, v2
	v_mov_b32_e32 v15, v2
	v_mov_b32_e32 v16, v2
	v_mov_b32_e32 v17, v2
	v_mov_b32_e32 v34, v2
	v_mov_b32_e32 v35, v2
	v_mov_b32_e32 v36, v2
	v_mov_b32_e32 v37, v2
	v_mov_b32_e32 v38, v2
	v_mov_b32_e32 v39, v2
	v_mov_b32_e32 v40, v2
	v_mov_b32_e32 v41, v2
	v_mov_b32_e32 v46, v2
	v_mov_b32_e32 v47, v2
	v_mov_b32_e32 v48, v2
	v_mov_b32_e32 v49, v2
	v_mov_b32_e32 v50, v2
	v_mov_b32_e32 v51, v2
	v_mov_b32_e32 v52, v2
	v_mov_b32_e32 v53, v2
	v_mov_b32_e32 v18, v2
	v_mov_b32_e32 v19, v2
	v_mov_b32_e32 v20, v2
	v_mov_b32_e32 v21, v2
	v_mov_b32_e32 v22, v2
	v_mov_b32_e32 v23, v2
	v_mov_b32_e32 v24, v2
	v_mov_b32_e32 v25, v2
	v_mov_b32_e32 v26, v2
	v_mov_b32_e32 v27, v2
	v_mov_b32_e32 v28, v2
	v_mov_b32_e32 v29, v2
	v_mov_b32_e32 v30, v2
	v_mov_b32_e32 v31, v2
	v_mov_b32_e32 v32, v2
	v_mov_b32_e32 v33, v2
	v_mov_b32_e32 v42, v2
	v_mov_b32_e32 v43, v2
	v_mov_b32_e32 v44, v2
	v_mov_b32_e32 v45, v2
	v_mov_b32_e32 v54, v2
	v_mov_b32_e32 v55, v2
	v_mov_b32_e32 v56, v2
	v_mov_b32_e32 v57, v2
	v_mov_b32_e32 v58, v2
	v_mov_b32_e32 v59, v2
	v_mov_b32_e32 v60, v2
	v_mov_b32_e32 v61, v2
	v_mov_b32_e32 v62, v2
	v_mov_b32_e32 v63, v2
	v_mov_b32_e32 v64, v2
	v_mov_b32_e32 v65, v2
	v_mov_b32_e32 v66, v2
	v_mov_b32_e32 v67, v2
	v_mov_b32_e32 v68, v2
	v_mov_b32_e32 v69, v2
	v_mov_b32_e32 v70, v2
	v_mov_b32_e32 v71, v2
	v_mov_b32_e32 v72, v2
	v_mov_b32_e32 v73, v2
	v_mov_b32_e32 v78, v2
	v_mov_b32_e32 v79, v2
	v_mov_b32_e32 v80, v2
	v_mov_b32_e32 v81, v2
	v_mov_b32_e32 v82, v2
	v_mov_b32_e32 v83, v2
	v_mov_b32_e32 v84, v2
	v_mov_b32_e32 v85, v2
	v_mov_b32_e32 v114, v2
	v_mov_b32_e32 v115, v2
	v_mov_b32_e32 v116, v2
	v_mov_b32_e32 v117, v2
	v_mov_b32_e32 v118, v2
	v_mov_b32_e32 v119, v2
	v_mov_b32_e32 v120, v2
	v_mov_b32_e32 v121, v2
	v_mov_b32_e32 v126, v2
	v_mov_b32_e32 v127, v2
	v_mov_b32_e32 v128, v2
	v_mov_b32_e32 v129, v2
	v_mov_b32_e32 v130, v2
	v_mov_b32_e32 v131, v2
	v_mov_b32_e32 v132, v2
	v_mov_b32_e32 v133, v2
	v_mov_b32_e32 v74, v2
	v_mov_b32_e32 v75, v2
	v_mov_b32_e32 v76, v2
	v_mov_b32_e32 v77, v2
	v_mov_b32_e32 v86, v2
	v_mov_b32_e32 v87, v2
	v_mov_b32_e32 v88, v2
	v_mov_b32_e32 v89, v2
	v_mov_b32_e32 v90, v2
	v_mov_b32_e32 v91, v2
	v_mov_b32_e32 v92, v2
	v_mov_b32_e32 v93, v2
	v_mov_b32_e32 v94, v2
	v_mov_b32_e32 v95, v2
	v_mov_b32_e32 v96, v2
	v_mov_b32_e32 v97, v2
	v_mov_b32_e32 v122, v2
	v_mov_b32_e32 v123, v2
	v_mov_b32_e32 v124, v2
	v_mov_b32_e32 v125, v2
	v_mov_b32_e32 v134, v2
	v_mov_b32_e32 v135, v2
	v_mov_b32_e32 v136, v2
	v_mov_b32_e32 v137, v2
	v_mov_b32_e32 v138, v2
	v_mov_b32_e32 v139, v2
	v_mov_b32_e32 v140, v2
	v_mov_b32_e32 v141, v2
	v_mov_b32_e32 v142, v2
	v_mov_b32_e32 v143, v2
	v_mov_b32_e32 v144, v2
	v_mov_b32_e32 v145, v2
	v_cmp_gt_u32_e32 vcc, 0x100, v163
	s_nop 1
	s_cbranch_vccz .Lsprio_skip1
	s_setprio 1

.LBB0_723:
	s_cmp_eq_u32 s27, 0
	s_cselect_b32 s99, 2, 0
	s_cmp_eq_u32 s27, 1
	s_cselect_b32 s99, 4, s99
	s_add_i32 s98, s99, -2
	s_add_u32 s28, s12, 0x100
	v_mov_b32_e32 v2, 0
	s_addc_u32 s29, s13, 0
	s_mov_b32 s30, -2
	v_mov_b32_e32 v3, v2
	v_mov_b32_e32 v4, v2
	v_mov_b32_e32 v5, v2
	v_mov_b32_e32 v6, v2
	v_mov_b32_e32 v7, v2
	v_mov_b32_e32 v8, v2
	v_mov_b32_e32 v9, v2
	v_mov_b32_e32 v18, v2
	v_mov_b32_e32 v19, v2
	v_mov_b32_e32 v20, v2
	v_mov_b32_e32 v21, v2
	v_mov_b32_e32 v22, v2
	v_mov_b32_e32 v23, v2
	v_mov_b32_e32 v24, v2
	v_mov_b32_e32 v25, v2
	v_mov_b32_e32 v34, v2
	v_mov_b32_e32 v35, v2
	v_mov_b32_e32 v36, v2
	v_mov_b32_e32 v37, v2
	v_mov_b32_e32 v38, v2
	v_mov_b32_e32 v39, v2
	v_mov_b32_e32 v40, v2
	v_mov_b32_e32 v41, v2
	v_mov_b32_e32 v50, v2
	v_mov_b32_e32 v51, v2
	v_mov_b32_e32 v52, v2
	v_mov_b32_e32 v53, v2
	v_mov_b32_e32 v54, v2
	v_mov_b32_e32 v55, v2
	v_mov_b32_e32 v56, v2
	v_mov_b32_e32 v57, v2
	v_mov_b32_e32 v10, v2
	v_mov_b32_e32 v11, v2
	v_mov_b32_e32 v12, v2
	v_mov_b32_e32 v13, v2
	v_mov_b32_e32 v14, v2
	v_mov_b32_e32 v15, v2
	v_mov_b32_e32 v16, v2
	v_mov_b32_e32 v17, v2
	v_mov_b32_e32 v26, v2
	v_mov_b32_e32 v27, v2
	v_mov_b32_e32 v28, v2
	v_mov_b32_e32 v29, v2
	v_mov_b32_e32 v30, v2
	v_mov_b32_e32 v31, v2
	v_mov_b32_e32 v32, v2
	v_mov_b32_e32 v33, v2
	v_mov_b32_e32 v42, v2
	v_mov_b32_e32 v43, v2
	v_mov_b32_e32 v44, v2
	v_mov_b32_e32 v45, v2
	v_mov_b32_e32 v46, v2
	v_mov_b32_e32 v47, v2
	v_mov_b32_e32 v48, v2
	v_mov_b32_e32 v49, v2
	v_mov_b32_e32 v58, v2
	v_mov_b32_e32 v59, v2
	v_mov_b32_e32 v60, v2
	v_mov_b32_e32 v61, v2
	v_mov_b32_e32 v62, v2
	v_mov_b32_e32 v63, v2
	v_mov_b32_e32 v64, v2
	v_mov_b32_e32 v65, v2
	v_mov_b32_e32 v66, v2
	v_mov_b32_e32 v67, v2
	v_mov_b32_e32 v68, v2
	v_mov_b32_e32 v69, v2
	v_mov_b32_e32 v70, v2
	v_mov_b32_e32 v71, v2
	v_mov_b32_e32 v72, v2
	v_mov_b32_e32 v73, v2
	v_mov_b32_e32 v82, v2
	v_mov_b32_e32 v83, v2
	v_mov_b32_e32 v84, v2
	v_mov_b32_e32 v85, v2
	v_mov_b32_e32 v86, v2
	v_mov_b32_e32 v87, v2
	v_mov_b32_e32 v88, v2
	v_mov_b32_e32 v89, v2
	v_mov_b32_e32 v98, v2
	v_mov_b32_e32 v99, v2
	v_mov_b32_e32 v100, v2
	v_mov_b32_e32 v101, v2
	v_mov_b32_e32 v102, v2
	v_mov_b32_e32 v103, v2
	v_mov_b32_e32 v104, v2
	v_mov_b32_e32 v105, v2
	v_mov_b32_e32 v114, v2
	v_mov_b32_e32 v115, v2
	v_mov_b32_e32 v116, v2
	v_mov_b32_e32 v117, v2
	v_mov_b32_e32 v118, v2
	v_mov_b32_e32 v119, v2
	v_mov_b32_e32 v120, v2
	v_mov_b32_e32 v121, v2
	v_mov_b32_e32 v74, v2
	v_mov_b32_e32 v75, v2
	v_mov_b32_e32 v76, v2
	v_mov_b32_e32 v77, v2
	v_mov_b32_e32 v78, v2
	v_mov_b32_e32 v79, v2
	v_mov_b32_e32 v80, v2
	v_mov_b32_e32 v81, v2
	v_mov_b32_e32 v90, v2
	v_mov_b32_e32 v91, v2
	v_mov_b32_e32 v92, v2
	v_mov_b32_e32 v93, v2
	v_mov_b32_e32 v94, v2
	v_mov_b32_e32 v95, v2
	v_mov_b32_e32 v96, v2
	v_mov_b32_e32 v97, v2
	v_mov_b32_e32 v106, v2
	v_mov_b32_e32 v107, v2
	v_mov_b32_e32 v108, v2
	v_mov_b32_e32 v109, v2
	v_mov_b32_e32 v110, v2
	v_mov_b32_e32 v111, v2
	v_mov_b32_e32 v112, v2
	v_mov_b32_e32 v113, v2
	v_mov_b32_e32 v122, v2
	v_mov_b32_e32 v123, v2
	v_mov_b32_e32 v124, v2
	v_mov_b32_e32 v125, v2
	v_mov_b32_e32 v126, v2
	v_mov_b32_e32 v127, v2
	v_mov_b32_e32 v128, v2
	v_mov_b32_e32 v129, v2
	v_cmp_gt_u32_e32 vcc, 0x100, v163
	s_nop 1
	s_cbranch_vccz .Lsprio_skip2
	s_setprio 1

.LBB0_892:
	s_ashr_i32 s13, s12, 31
	v_cmp_lt_i64_e32 vcc, s[16:17], v[166:167]
	s_lshl_b64 s[16:17], s[12:13], 18
	s_add_u32 s16, s3, s16
	s_addc_u32 s17, s24, s17
	s_and_b32 s98, s10, 1
	s_lshl_b32 s98, s98, 9
	s_add_u32 s16, s16, s98
	s_addc_u32 s17, s17, 0
	v_readlane_b32 s98, v254, 0
	s_and_b32 s98, s98, s99
	s_lshl_b32 s98, s98, 17
	s_add_u32 s16, s16, s98
	s_addc_u32 s17, s17, 0
	s_and_b32 s98, s10, 1
	s_lshl_b32 s98, s98, 9
	s_and_b64 s[18:19], vcc, exec
	s_cselect_b32 s13, s17, s21
	s_cselect_b32 s39, s16, s20
	s_ashr_i32 s11, s10, 31
	s_lshl_b64 s[18:19], s[10:11], 18
	s_add_u32 s18, s25, s18
	s_addc_u32 s19, s26, s19
	s_add_u32 s18, s18, s98
	s_addc_u32 s19, s19, 0
	s_and_b64 s[22:23], vcc, exec
	s_cselect_b32 s11, s19, s9
	s_cselect_b32 s40, s18, s8
	s_add_u32 s41, s8, 0x100
	s_addc_u32 s42, s9, 0
	s_add_u32 s8, s20, 0x20080
	v_mov_b32_e32 v2, 0
	s_addc_u32 s9, s21, 0
	s_mov_b32 s43, -2
	v_mov_b32_e32 v3, v2
	v_mov_b32_e32 v4, v2
	v_mov_b32_e32 v5, v2
	v_mov_b32_e32 v6, v2
	v_mov_b32_e32 v7, v2
	v_mov_b32_e32 v8, v2
	v_mov_b32_e32 v9, v2
	v_mov_b32_e32 v14, v2
	v_mov_b32_e32 v15, v2
	v_mov_b32_e32 v16, v2
	v_mov_b32_e32 v17, v2
	v_mov_b32_e32 v22, v2
	v_mov_b32_e32 v23, v2
	v_mov_b32_e32 v24, v2
	v_mov_b32_e32 v25, v2
	v_mov_b32_e32 v30, v2
	v_mov_b32_e32 v31, v2
	v_mov_b32_e32 v32, v2
	v_mov_b32_e32 v33, v2
	v_mov_b32_e32 v38, v2
	v_mov_b32_e32 v39, v2
	v_mov_b32_e32 v40, v2
	v_mov_b32_e32 v41, v2
	v_mov_b32_e32 v46, v2
	v_mov_b32_e32 v47, v2
	v_mov_b32_e32 v48, v2
	v_mov_b32_e32 v49, v2
	v_mov_b32_e32 v54, v2
	v_mov_b32_e32 v55, v2
	v_mov_b32_e32 v56, v2
	v_mov_b32_e32 v57, v2
	v_mov_b32_e32 v10, v2
	v_mov_b32_e32 v11, v2
	v_mov_b32_e32 v12, v2
	v_mov_b32_e32 v13, v2
	v_mov_b32_e32 v18, v2
	v_mov_b32_e32 v19, v2
	v_mov_b32_e32 v20, v2
	v_mov_b32_e32 v21, v2
	v_mov_b32_e32 v26, v2
	v_mov_b32_e32 v27, v2
	v_mov_b32_e32 v28, v2
	v_mov_b32_e32 v29, v2
	v_mov_b32_e32 v34, v2
	v_mov_b32_e32 v35, v2
	v_mov_b32_e32 v36, v2
	v_mov_b32_e32 v37, v2
	v_mov_b32_e32 v42, v2
	v_mov_b32_e32 v43, v2
	v_mov_b32_e32 v44, v2
	v_mov_b32_e32 v45, v2
	v_mov_b32_e32 v50, v2
	v_mov_b32_e32 v51, v2
	v_mov_b32_e32 v52, v2
	v_mov_b32_e32 v53, v2
	v_mov_b32_e32 v58, v2
	v_mov_b32_e32 v59, v2
	v_mov_b32_e32 v60, v2
	v_mov_b32_e32 v61, v2
	v_mov_b32_e32 v62, v2
	v_mov_b32_e32 v63, v2
	v_mov_b32_e32 v64, v2
	v_mov_b32_e32 v65, v2
	v_mov_b32_e32 v66, v2
	v_mov_b32_e32 v67, v2
	v_mov_b32_e32 v68, v2
	v_mov_b32_e32 v69, v2
	v_mov_b32_e32 v70, v2
	v_mov_b32_e32 v71, v2
	v_mov_b32_e32 v72, v2
	v_mov_b32_e32 v73, v2
	v_mov_b32_e32 v78, v2
	v_mov_b32_e32 v79, v2
	v_mov_b32_e32 v80, v2
	v_mov_b32_e32 v81, v2
	v_mov_b32_e32 v86, v2
	v_mov_b32_e32 v87, v2
	v_mov_b32_e32 v88, v2
	v_mov_b32_e32 v89, v2
	v_mov_b32_e32 v94, v2
	v_mov_b32_e32 v95, v2
	v_mov_b32_e32 v96, v2
	v_mov_b32_e32 v97, v2
	v_mov_b32_e32 v102, v2
	v_mov_b32_e32 v103, v2
	v_mov_b32_e32 v104, v2
	v_mov_b32_e32 v105, v2
	v_mov_b32_e32 v110, v2
	v_mov_b32_e32 v111, v2
	v_mov_b32_e32 v112, v2
	v_mov_b32_e32 v113, v2
	v_mov_b32_e32 v118, v2
	v_mov_b32_e32 v119, v2
	v_mov_b32_e32 v120, v2
	v_mov_b32_e32 v121, v2
	v_mov_b32_e32 v74, v2
	v_mov_b32_e32 v75, v2
	v_mov_b32_e32 v76, v2
	v_mov_b32_e32 v77, v2
	v_mov_b32_e32 v82, v2
	v_mov_b32_e32 v83, v2
	v_mov_b32_e32 v84, v2
	v_mov_b32_e32 v85, v2
	v_mov_b32_e32 v90, v2
	v_mov_b32_e32 v91, v2
	v_mov_b32_e32 v92, v2
	v_mov_b32_e32 v93, v2
	v_mov_b32_e32 v98, v2
	v_mov_b32_e32 v99, v2
	v_mov_b32_e32 v100, v2
	v_mov_b32_e32 v101, v2
	v_mov_b32_e32 v106, v2
	v_mov_b32_e32 v107, v2
	v_mov_b32_e32 v108, v2
	v_mov_b32_e32 v109, v2
	v_mov_b32_e32 v114, v2
	v_mov_b32_e32 v115, v2
	v_mov_b32_e32 v116, v2
	v_mov_b32_e32 v117, v2
	v_mov_b32_e32 v122, v2
	v_mov_b32_e32 v123, v2
	v_mov_b32_e32 v124, v2
	v_mov_b32_e32 v125, v2
	v_mov_b32_e32 v126, v2
	v_mov_b32_e32 v127, v2
	v_mov_b32_e32 v128, v2
	v_mov_b32_e32 v129, v2
	v_readlane_b32 s99, v255, 41
	s_cmp_eq_u32 s38, 2
	s_cselect_b32 s99, s99, 0
	v_cmp_gt_u32_e32 vcc, 0x100, v163
	s_nop 1
	s_cbranch_vccz .Lsprio_skip3
	s_setprio 1

.LBB0_917:
	v_mov_b64_e32 v[2:3], 0x3c0
	s_ashr_i32 s21, s20, 31
	v_cmp_lt_i64_e32 vcc, s[22:23], v[2:3]
	s_lshl_b64 s[22:23], s[20:21], 19
	v_readlane_b32 s24, v254, 33
	v_readlane_b32 s25, v254, 34
	s_add_u32 s22, s24, s22
	s_addc_u32 s23, s25, s23
	s_and_b64 s[24:25], vcc, exec
	s_cselect_b32 s7, s23, s29
	s_cselect_b32 s9, s22, s28
	s_ashr_i32 s19, s18, 31
	s_lshl_b64 s[24:25], s[18:19], 19
	s_add_u32 s24, s3, s24
	s_addc_u32 s25, s36, s25
	s_and_b64 s[30:31], vcc, exec
	s_cselect_b32 s19, s25, s27
	s_cselect_b32 s21, s24, s26
	s_add_u32 s34, s26, 0x100
	s_addc_u32 s35, s27, 0
	s_add_u32 s26, s28, 0x40080
	v_mov_b32_e32 v2, 0
	s_addc_u32 s27, s29, 0
	s_mov_b32 s47, -2
	v_mov_b32_e32 v3, v2
	v_mov_b32_e32 v4, v2
	v_mov_b32_e32 v5, v2
	v_mov_b32_e32 v6, v2
	v_mov_b32_e32 v7, v2
	v_mov_b32_e32 v8, v2
	v_mov_b32_e32 v9, v2
	v_mov_b32_e32 v18, v2
	v_mov_b32_e32 v19, v2
	v_mov_b32_e32 v20, v2
	v_mov_b32_e32 v21, v2
	v_mov_b32_e32 v22, v2
	v_mov_b32_e32 v23, v2
	v_mov_b32_e32 v24, v2
	v_mov_b32_e32 v25, v2
	v_mov_b32_e32 v34, v2
	v_mov_b32_e32 v35, v2
	v_mov_b32_e32 v36, v2
	v_mov_b32_e32 v37, v2
	v_mov_b32_e32 v38, v2
	v_mov_b32_e32 v39, v2
	v_mov_b32_e32 v40, v2
	v_mov_b32_e32 v41, v2
	v_mov_b32_e32 v50, v2
	v_mov_b32_e32 v51, v2
	v_mov_b32_e32 v52, v2
	v_mov_b32_e32 v53, v2
	v_mov_b32_e32 v54, v2
	v_mov_b32_e32 v55, v2
	v_mov_b32_e32 v56, v2
	v_mov_b32_e32 v57, v2
	v_mov_b32_e32 v10, v2
	v_mov_b32_e32 v11, v2
	v_mov_b32_e32 v12, v2
	v_mov_b32_e32 v13, v2
	v_mov_b32_e32 v14, v2
	v_mov_b32_e32 v15, v2
	v_mov_b32_e32 v16, v2
	v_mov_b32_e32 v17, v2
	v_mov_b32_e32 v26, v2
	v_mov_b32_e32 v27, v2
	v_mov_b32_e32 v28, v2
	v_mov_b32_e32 v29, v2
	v_mov_b32_e32 v30, v2
	v_mov_b32_e32 v31, v2
	v_mov_b32_e32 v32, v2
	v_mov_b32_e32 v33, v2
	v_mov_b32_e32 v42, v2
	v_mov_b32_e32 v43, v2
	v_mov_b32_e32 v44, v2
	v_mov_b32_e32 v45, v2
	v_mov_b32_e32 v46, v2
	v_mov_b32_e32 v47, v2
	v_mov_b32_e32 v48, v2
	v_mov_b32_e32 v49, v2
	v_mov_b32_e32 v58, v2
	v_mov_b32_e32 v59, v2
	v_mov_b32_e32 v60, v2
	v_mov_b32_e32 v61, v2
	v_mov_b32_e32 v62, v2
	v_mov_b32_e32 v63, v2
	v_mov_b32_e32 v64, v2
	v_mov_b32_e32 v65, v2
	v_mov_b32_e32 v66, v2
	v_mov_b32_e32 v67, v2
	v_mov_b32_e32 v68, v2
	v_mov_b32_e32 v69, v2
	v_mov_b32_e32 v70, v2
	v_mov_b32_e32 v71, v2
	v_mov_b32_e32 v72, v2
	v_mov_b32_e32 v73, v2
	v_mov_b32_e32 v82, v2
	v_mov_b32_e32 v83, v2
	v_mov_b32_e32 v84, v2
	v_mov_b32_e32 v85, v2
	v_mov_b32_e32 v86, v2
	v_mov_b32_e32 v87, v2
	v_mov_b32_e32 v88, v2
	v_mov_b32_e32 v89, v2
	v_mov_b32_e32 v98, v2
	v_mov_b32_e32 v99, v2
	v_mov_b32_e32 v100, v2
	v_mov_b32_e32 v101, v2
	v_mov_b32_e32 v102, v2
	v_mov_b32_e32 v103, v2
	v_mov_b32_e32 v104, v2
	v_mov_b32_e32 v105, v2
	v_mov_b32_e32 v114, v2
	v_mov_b32_e32 v115, v2
	v_mov_b32_e32 v116, v2
	v_mov_b32_e32 v117, v2
	v_mov_b32_e32 v118, v2
	v_mov_b32_e32 v119, v2
	v_mov_b32_e32 v120, v2
	v_mov_b32_e32 v121, v2
	v_mov_b32_e32 v74, v2
	v_mov_b32_e32 v75, v2
	v_mov_b32_e32 v76, v2
	v_mov_b32_e32 v77, v2
	v_mov_b32_e32 v78, v2
	v_mov_b32_e32 v79, v2
	v_mov_b32_e32 v80, v2
	v_mov_b32_e32 v81, v2
	v_mov_b32_e32 v90, v2
	v_mov_b32_e32 v91, v2
	v_mov_b32_e32 v92, v2
	v_mov_b32_e32 v93, v2
	v_mov_b32_e32 v94, v2
	v_mov_b32_e32 v95, v2
	v_mov_b32_e32 v96, v2
	v_mov_b32_e32 v97, v2
	v_mov_b32_e32 v106, v2
	v_mov_b32_e32 v107, v2
	v_mov_b32_e32 v108, v2
	v_mov_b32_e32 v109, v2
	v_mov_b32_e32 v110, v2
	v_mov_b32_e32 v111, v2
	v_mov_b32_e32 v112, v2
	v_mov_b32_e32 v113, v2
	v_mov_b32_e32 v122, v2
	v_mov_b32_e32 v123, v2
	v_mov_b32_e32 v124, v2
	v_mov_b32_e32 v125, v2
	v_mov_b32_e32 v126, v2
	v_mov_b32_e32 v127, v2
	v_mov_b32_e32 v128, v2
	v_mov_b32_e32 v129, v2
	v_cmp_gt_u32_e32 vcc, 0x100, v163
	s_nop 1
	s_cbranch_vccz .Lsprio_skip4
	s_setprio 1

.LBB0_1246:
	s_add_u32 s41, s16, 0x100
	v_mov_b32_e32 v2, 0
	s_addc_u32 s42, s17, 0
	s_mov_b32 s43, -2
	v_mov_b32_e32 v3, v2
	v_mov_b32_e32 v4, v2
	v_mov_b32_e32 v5, v2
	v_mov_b32_e32 v6, v2
	v_mov_b32_e32 v7, v2
	v_mov_b32_e32 v8, v2
	v_mov_b32_e32 v9, v2
	v_mov_b32_e32 v10, v2
	v_mov_b32_e32 v11, v2
	v_mov_b32_e32 v12, v2
	v_mov_b32_e32 v13, v2
	v_mov_b32_e32 v14, v2
	v_mov_b32_e32 v15, v2
	v_mov_b32_e32 v16, v2
	v_mov_b32_e32 v17, v2
	v_mov_b32_e32 v34, v2
	v_mov_b32_e32 v35, v2
	v_mov_b32_e32 v36, v2
	v_mov_b32_e32 v37, v2
	v_mov_b32_e32 v38, v2
	v_mov_b32_e32 v39, v2
	v_mov_b32_e32 v40, v2
	v_mov_b32_e32 v41, v2
	v_mov_b32_e32 v46, v2
	v_mov_b32_e32 v47, v2
	v_mov_b32_e32 v48, v2
	v_mov_b32_e32 v49, v2
	v_mov_b32_e32 v50, v2
	v_mov_b32_e32 v51, v2
	v_mov_b32_e32 v52, v2
	v_mov_b32_e32 v53, v2
	v_mov_b32_e32 v18, v2
	v_mov_b32_e32 v19, v2
	v_mov_b32_e32 v20, v2
	v_mov_b32_e32 v21, v2
	v_mov_b32_e32 v22, v2
	v_mov_b32_e32 v23, v2
	v_mov_b32_e32 v24, v2
	v_mov_b32_e32 v25, v2
	v_mov_b32_e32 v26, v2
	v_mov_b32_e32 v27, v2
	v_mov_b32_e32 v28, v2
	v_mov_b32_e32 v29, v2
	v_mov_b32_e32 v30, v2
	v_mov_b32_e32 v31, v2
	v_mov_b32_e32 v32, v2
	v_mov_b32_e32 v33, v2
	v_mov_b32_e32 v42, v2
	v_mov_b32_e32 v43, v2
	v_mov_b32_e32 v44, v2
	v_mov_b32_e32 v45, v2
	v_mov_b32_e32 v54, v2
	v_mov_b32_e32 v55, v2
	v_mov_b32_e32 v56, v2
	v_mov_b32_e32 v57, v2
	v_mov_b32_e32 v58, v2
	v_mov_b32_e32 v59, v2
	v_mov_b32_e32 v60, v2
	v_mov_b32_e32 v61, v2
	v_mov_b32_e32 v62, v2
	v_mov_b32_e32 v63, v2
	v_mov_b32_e32 v64, v2
	v_mov_b32_e32 v65, v2
	v_mov_b32_e32 v66, v2
	v_mov_b32_e32 v67, v2
	v_mov_b32_e32 v68, v2
	v_mov_b32_e32 v69, v2
	v_mov_b32_e32 v70, v2
	v_mov_b32_e32 v71, v2
	v_mov_b32_e32 v72, v2
	v_mov_b32_e32 v73, v2
	v_mov_b32_e32 v78, v2
	v_mov_b32_e32 v79, v2
	v_mov_b32_e32 v80, v2
	v_mov_b32_e32 v81, v2
	v_mov_b32_e32 v82, v2
	v_mov_b32_e32 v83, v2
	v_mov_b32_e32 v84, v2
	v_mov_b32_e32 v85, v2
	v_mov_b32_e32 v114, v2
	v_mov_b32_e32 v115, v2
	v_mov_b32_e32 v116, v2
	v_mov_b32_e32 v117, v2
	v_mov_b32_e32 v118, v2
	v_mov_b32_e32 v119, v2
	v_mov_b32_e32 v120, v2
	v_mov_b32_e32 v121, v2
	v_mov_b32_e32 v126, v2
	v_mov_b32_e32 v127, v2
	v_mov_b32_e32 v128, v2
	v_mov_b32_e32 v129, v2
	v_mov_b32_e32 v130, v2
	v_mov_b32_e32 v131, v2
	v_mov_b32_e32 v132, v2
	v_mov_b32_e32 v133, v2
	v_mov_b32_e32 v74, v2
	v_mov_b32_e32 v75, v2
	v_mov_b32_e32 v76, v2
	v_mov_b32_e32 v77, v2
	v_mov_b32_e32 v86, v2
	v_mov_b32_e32 v87, v2
	v_mov_b32_e32 v88, v2
	v_mov_b32_e32 v89, v2
	v_mov_b32_e32 v90, v2
	v_mov_b32_e32 v91, v2
	v_mov_b32_e32 v92, v2
	v_mov_b32_e32 v93, v2
	v_mov_b32_e32 v94, v2
	v_mov_b32_e32 v95, v2
	v_mov_b32_e32 v96, v2
	v_mov_b32_e32 v97, v2
	v_mov_b32_e32 v122, v2
	v_mov_b32_e32 v123, v2
	v_mov_b32_e32 v124, v2
	v_mov_b32_e32 v125, v2
	v_mov_b32_e32 v134, v2
	v_mov_b32_e32 v135, v2
	v_mov_b32_e32 v136, v2
	v_mov_b32_e32 v137, v2
	v_mov_b32_e32 v138, v2
	v_mov_b32_e32 v139, v2
	v_mov_b32_e32 v140, v2
	v_mov_b32_e32 v141, v2
	v_mov_b32_e32 v142, v2
	v_mov_b32_e32 v143, v2
	v_mov_b32_e32 v144, v2
	v_mov_b32_e32 v145, v2
	v_readlane_b32 s99, v255, 41
	s_cmp_eq_u32 s36, 2
	s_cselect_b32 s99, s99, 0
	v_cmp_gt_u32_e32 vcc, 0x100, v163
	s_nop 1
	s_cbranch_vccz .Lsprio_skip5
	s_setprio 1
